# phase 11: staggered wave halves (2 barriers per tile, 3 LDS buffers) + XCD-aware unit mapping so each XCD reads only its own heads K/V
# speedup vs baseline: 1.0012x; 1.0012x over previous
; __device__ __forceinline__ void phase_na(const Params& p, unsigned char* lds) {
;     const int tid = threadIdx.x, lane = tid & 63, w = __builtin_amdgcn_readfirstlane(tid >> 6), fr = lane & 15, fq = lane >> 4;
;     bf16_t* KtB = (bf16_t*)(lds + NA_KT); bf16_t* vtB = (bf16_t*)(lds + NA_VT); bf16_t* Pw = (bf16_t*)(lds + NA_PW) + w * (32 * 72); float* rbt = (float*)(lds + NA_RB);
;     const bf16_t* QK = (const bf16_t*)(p.ws + WS_P); const bf16_t* VTg = (const bf16_t*)(p.ws + WS_VT); bf16_t* O = (bf16_t*)(p.ws + WS_A);
;     const int key = tid >> 3, part = tid & 7;
;     const int vd = tid >> 2, vc4 = tid & 3;
;     const float scale = 0.08838834764831845f * 1.4426950408889634f;
;     for (int u = blockIdx.x; u < 1024; u += gridDim.x) {
;         const int r4 = u & 15, h = (u >> 4) & 15, b = u >> 8, r0 = 4 * r4;
;         const int rs_lo = min(max(r0 - 4, 0), 56), rs_hi = min(max(r0 - 1, 0), 56);
;         const int ntile = 4 + (rs_hi + 8 - rs_lo);
;         const int qr = r0 + (w >> 1), qc0 = 32 * (w & 1);
;         const int rsq = min(max(qr - 4, 0), 56);
;     ...
;                 const int wlo0 = min(max(qc0 - 8, 0), 48), whi0 = min(max(qc0 + 7, 0), 48) + 16, wlo1 = min(max(qc0 + 8, 0), 48), whi1 = min(max(qc0 + 23, 0), 48) + 16;
; #pragma unroll
;                 for (int nt = 0; nt < 4; ++nt) {
;                     const bool act0 = !band || (16 * nt < whi0 && 16 * nt + 16 > wlo0), act1 = !band || (16 * nt < whi1 && 16 * nt + 16 > wlo1);
;                     st[0][nt] = (f32x4){0.f, 0.f, 0.f, 0.f}; st[1][nt] = (f32x4){0.f, 0.f, 0.f, 0.f};
;                     if (act0 || act1) {
;                         bf16x8 Bk[4];
; #pragma unroll
;                         for (int ks = 0; ks < 4; ++ks) Bk[ks] = *(const bf16x8*)(Kt + (nt * 16 + fr) * 136 + ks * 32 + fq * 8);
; #pragma unroll
;                         for (int ks = 0; ks < 4; ++ks) {
;                             if (act0) st[0][nt] = __builtin_amdgcn_mfma_f32_16x16x32_bf16(Bk[ks], aq[0][ks], st[0][nt], 0, 0, 0);
;                             if (act1) st[1][nt] = __builtin_amdgcn_mfma_f32_16x16x32_bf16(Bk[ks], aq[1][ks], st[1][nt], 0, 0, 0); }
;                     }
;                 }
;                 unsigned pk[2][4][2];
; #pragma unroll
;                 for (int mt = 0; mt < 2; ++mt) {
;                     __builtin_amdgcn_sched_barrier(0);
.Lna_begin:
	v_readfirstlane_b32 s10, v162
	s_add_u32 s4, s90, 0x10a00000
	s_addc_u32 s5, s91, 0
	s_add_u32 s6, s90, 0x19c00000
	s_addc_u32 s7, s91, 0
	s_add_u32 s8, s90, 0xc600000
	s_addc_u32 s9, s91, 0
	s_lshr_b32 s10, s10, 6
	s_lshr_b32 s11, s10, 1
	s_and_b32 s12, s10, 1
	s_lshl_b32 s12, s12, 5
	s_mov_b32 s30, 0x3e0293ee
	s_mov_b32 s31, 0xf149f2ca
	v_and_b32_e32 v232, 63, v162
	v_and_b32_e32 v233, 15, v232
	v_lshrrev_b32_e32 v234, 4, v232
	v_lshrrev_b32_e32 v235, 3, v162
	v_and_b32_e32 v236, 7, v162
	v_lshlrev_b32_e32 v237, 5, v236
	v_lshl_or_b32 v163, v235, 13, v237
	v_mul_u32_u24_e32 v238, 0x110, v235
	v_add_u32_e32 v164, v238, v237
	v_lshrrev_b32_e32 v235, 2, v162
	v_and_b32_e32 v236, 3, v162
	v_lshlrev_b32_e32 v237, 5, v236
	v_mul_u32_u24_e32 v238, 0x8800, v235
	v_add_u32_e32 v165, v238, v237
	v_mul_u32_u24_e32 v238, 0x90, v235
	v_add_u32_e32 v238, v238, v237
	v_add_u32_e32 v166, 52224, v238
	v_mul_u32_u24_e32 v238, 0x110, v233
	v_lshl_add_u32 v167, v234, 4, v238
	v_mul_u32_u24_e32 v238, 0x90, v233
	v_lshl_add_u32 v238, v234, 3, v238
	v_add_u32_e32 v168, 52224, v238
	v_xor_b32_e32 v235, 16, v232
	v_lshlrev_b32_e32 v218, 2, v235
	v_xor_b32_e32 v235, 32, v232
	v_lshlrev_b32_e32 v219, 2, v235
	v_mov_b32_e32 v232, 0
	v_mov_b32_e32 v239, 0xf149f2ca
	v_add_u32_e32 v235, s12, v233
	v_sub_u32_e64 v236, v235, 8 clamp
	v_min_u32_e32 v236, 48, v236
	v_lshlrev_b32_e32 v237, 2, v234
	v_sub_u32_e32 v238, v237, v235
	v_lshlrev_b32_e32 v238, 2, v238
	v_add_u32_e32 v220, 110908, v238
	v_sub_u32_e32 v238, v237, v236
	v_add_u32_e32 v237, 0, v238
	v_cmp_gt_u32_e32 vcc, 16, v237
	v_cndmask_b32_e32 v186, v239, v232, vcc
	v_add_u32_e32 v237, 1, v238
	v_cmp_gt_u32_e32 vcc, 16, v237
	v_cndmask_b32_e32 v187, v239, v232, vcc
	v_add_u32_e32 v237, 2, v238
	v_cmp_gt_u32_e32 vcc, 16, v237
	v_cndmask_b32_e32 v188, v239, v232, vcc
	v_add_u32_e32 v237, 3, v238
	v_cmp_gt_u32_e32 vcc, 16, v237
	v_cndmask_b32_e32 v189, v239, v232, vcc
	v_add_u32_e32 v237, 16, v238
	v_cmp_gt_u32_e32 vcc, 16, v237
	v_cndmask_b32_e32 v190, v239, v232, vcc
	v_add_u32_e32 v237, 17, v238
	v_cmp_gt_u32_e32 vcc, 16, v237
	v_cndmask_b32_e32 v191, v239, v232, vcc
	v_add_u32_e32 v237, 18, v238
	v_cmp_gt_u32_e32 vcc, 16, v237
	v_cndmask_b32_e32 v192, v239, v232, vcc
	v_add_u32_e32 v237, 19, v238
	v_cmp_gt_u32_e32 vcc, 16, v237
	v_cndmask_b32_e32 v193, v239, v232, vcc
	v_add_u32_e32 v237, 32, v238
	v_cmp_gt_u32_e32 vcc, 16, v237
	v_cndmask_b32_e32 v194, v239, v232, vcc
	v_add_u32_e32 v237, 33, v238
	v_cmp_gt_u32_e32 vcc, 16, v237
	v_cndmask_b32_e32 v195, v239, v232, vcc
	v_add_u32_e32 v237, 34, v238
	v_cmp_gt_u32_e32 vcc, 16, v237
	v_cndmask_b32_e32 v196, v239, v232, vcc
	v_add_u32_e32 v237, 35, v238
	v_cmp_gt_u32_e32 vcc, 16, v237
	v_cndmask_b32_e32 v197, v239, v232, vcc
	v_add_u32_e32 v237, 48, v238
	v_cmp_gt_u32_e32 vcc, 16, v237
	v_cndmask_b32_e32 v198, v239, v232, vcc
	v_add_u32_e32 v237, 49, v238
	v_cmp_gt_u32_e32 vcc, 16, v237
	v_cndmask_b32_e32 v199, v239, v232, vcc
	v_add_u32_e32 v237, 50, v238
	v_cmp_gt_u32_e32 vcc, 16, v237
	v_cndmask_b32_e32 v200, v239, v232, vcc
	v_add_u32_e32 v237, 51, v238
	v_cmp_gt_u32_e32 vcc, 16, v237
	v_cndmask_b32_e32 v201, v239, v232, vcc
	v_add_u32_e32 v235, s12, v233
	v_add_u32_e32 v235, 16, v235
	v_sub_u32_e64 v236, v235, 8 clamp
	v_min_u32_e32 v236, 48, v236
	v_lshlrev_b32_e32 v237, 2, v234
	v_sub_u32_e32 v238, v237, v235
	v_lshlrev_b32_e32 v238, 2, v238
	v_add_u32_e32 v221, 110908, v238
	v_sub_u32_e32 v238, v237, v236
	v_add_u32_e32 v237, 0, v238
	v_cmp_gt_u32_e64 s[32:33], 16, v237
	v_add_u32_e32 v237, 1, v238
	v_cmp_gt_u32_e64 s[34:35], 16, v237
	v_add_u32_e32 v237, 2, v238
	v_cmp_gt_u32_e64 s[36:37], 16, v237
	v_add_u32_e32 v237, 3, v238
	v_cmp_gt_u32_e64 s[38:39], 16, v237
	v_add_u32_e32 v237, 16, v238
	v_cmp_gt_u32_e64 s[40:41], 16, v237
	v_add_u32_e32 v237, 17, v238
	v_cmp_gt_u32_e64 s[42:43], 16, v237
	v_add_u32_e32 v237, 18, v238
	v_cmp_gt_u32_e64 s[44:45], 16, v237
	v_add_u32_e32 v237, 19, v238
	v_cmp_gt_u32_e64 s[46:47], 16, v237
	v_add_u32_e32 v237, 32, v238
	v_cmp_gt_u32_e64 s[48:49], 16, v237
	v_add_u32_e32 v237, 33, v238
	v_cmp_gt_u32_e64 s[50:51], 16, v237
	v_add_u32_e32 v237, 34, v238
	v_cmp_gt_u32_e64 s[52:53], 16, v237
	v_add_u32_e32 v237, 35, v238
	v_cmp_gt_u32_e64 s[54:55], 16, v237
	v_add_u32_e32 v237, 48, v238
	v_cmp_gt_u32_e64 s[56:57], 16, v237
	v_add_u32_e32 v237, 49, v238
	v_cmp_gt_u32_e64 s[58:59], 16, v237
	v_add_u32_e32 v237, 50, v238
	v_cmp_gt_u32_e64 s[60:61], 16, v237
	v_add_u32_e32 v237, 51, v238
	v_cmp_gt_u32_e64 s[62:63], 16, v237
	v_lshlrev_b32_e32 v235, 2, v162
	v_add_u32_e32 v235, 110592, v235
	v_mov_b32_e32 v236, 0
	ds_write_b32 v235, v236
	v_cmp_gt_u32_e32 vcc, 128, v162
	s_and_saveexec_b64 s[0:1], vcc
	ds_write_b32 v235, v236 offset:2048
	s_mov_b64 exec, s[0:1]
	s_mov_b32 s13, s92
	s_waitcnt lgkmcnt(0)
; #define NA_WRITE(R, buf) do { bf16_t* kd = KtB + (buf) * (64 * 136) + key * 136 + part * 16; bf16_t* vdp = vtB + (buf) * (128 * 72) + vd * 72 + vc4 * 16; \
;         *(u32x4*)kd = R[0]; *(u32x4*)(kd + 8) = R[1]; *(u32x4*)vdp = R[2]; *(u32x4*)(vdp + 8) = R[3]; } while (0)
; __device__ __forceinline__ void phase_na(const Params& p, unsigned char* lds) {
;     ...
;     for (int u = blockIdx.x; u < 1024; u += gridDim.x) {
;         const int r4 = u & 15, h = (u >> 4) & 15, b = u >> 8, r0 = 4 * r4;
;         const int rs_lo = min(max(r0 - 4, 0), 56), rs_hi = min(max(r0 - 1, 0), 56);
;         const int ntile = 4 + (rs_hi + 8 - rs_lo);
;         const int qr = r0 + (w >> 1), qc0 = 32 * (w & 1);
;         const int rsq = min(max(qr - 4, 0), 56);
;         __syncthreads();
;         for (int e = tid; e < 465; e += 512) rbt[e] = p.rel_bias[h * 465 + e] * 1.4426950408889634f;
;         bf16x8 aq[2][4];
; #pragma unroll
;         for (int mt = 0; mt < 2; ++mt) { const bf16_t* qp = QK + (size_t)(b * SEQ + qr * 64 + qc0 + 16 * mt + fr) * NQK + h * 128 + fq * 8;
; #pragma unroll
;             for (int ks = 0; ks < 4; ++ks) aq[mt][ks] = *(const bf16x8*)(qp + ks * 32); }
;         f32x4 Oa[2][8];
; #pragma unroll
;         for (int mt = 0; mt < 2; ++mt)
; #pragma unroll
;             for (int dt = 0; dt < 8; ++dt) Oa[mt][dt] = (f32x4){0.f, 0.f, 0.f, 0.f};
;         float mrow[2] = {-1e30f, -1e30f}, lrow[2] = {0.f, 0.f};
;         u32x4 ra[4];
;     ...
;         { u32x4 rn[4];
;           NA_LOAD(ra, 0); NA_LOAD(rn, 1); NA_WRITE(ra, 0);
;           ra[0] = rn[0]; ra[1] = rn[1]; ra[2] = rn[2]; ra[3] = rn[3]; }
;         __syncthreads();
;         for (int kt = 0; kt < ntile; ++kt) {
;             if (kt + 1 < ntile) { NA_WRITE(ra, (kt + 1) & 1); if (kt + 2 < ntile) NA_LOAD(ra, kt + 2); }
.Lna_unit:
	s_cmp_ge_u32 s13, 0x400
	s_cbranch_scc1 .Lna_done
	s_lshr_b32 s15, s13, 8
	s_and_b32 s0, s13, 7
	s_bfe_u32 s1, s13, 0x50003
	s_lshr_b32 s14, s1, 4
	s_lshl_b32 s0, s0, 1
	s_or_b32 s14, s14, s0
	s_and_b32 s16, s1, 15
	s_lshl_b32 s16, s16, 2
	s_add_i32 s17, s16, -4
	s_max_i32 s17, s17, 0
	s_min_i32 s17, s17, 56
	s_add_i32 s18, s16, -1
	s_max_i32 s18, s18, 0
	s_min_i32 s18, s18, 56
	s_sub_i32 s18, s18, s17
	s_add_i32 s18, s18, 12
	s_add_i32 s19, s16, s11
	s_add_i32 s20, s19, -4
	s_max_i32 s20, s20, 0
	s_min_i32 s20, s20, 56
	s_barrier
	s_movk_i32 s0, 0x1d1
	v_cmp_gt_u32_e32 vcc, s0, v162
	s_and_saveexec_b64 s[2:3], vcc
	s_mul_i32 s0, s14, 0x1d1
	v_add_lshl_u32 v232, s0, v162, 2
	global_load_dword v234, v232, s[84:85]
	s_mov_b64 exec, s[2:3]
	s_mov_b32 s21, 0
	s_lshl_b32 s28, s15, 8
	s_add_i32 s28, s28, 0x4000
	s_lshl_b32 s29, s21, 6
	s_add_i32 s28, s28, s29
	s_add_i32 s29, s21, s17
	s_add_i32 s29, s29, -4
	s_lshl_b32 s29, s29, 6
	s_lshl_b32 s26, s15, 12
	s_add_i32 s29, s29, s26
	s_cmp_lt_u32 s21, 4
	s_cselect_b32 s28, s28, s29
	s_lshl_b32 s26, s28, 13
	s_lshl_b32 s29, s14, 8
	s_add_i32 s26, s26, s29
	s_add_i32 s26, s26, 0x1000
	s_lshl_b32 s27, s28, 1
	s_mul_i32 s29, s14, 0x440000
	s_add_i32 s27, s27, s29
	v_add_u32_e32 v238, s26, v163
	v_add_u32_e32 v239, s27, v165
	global_load_dwordx4 v[128:131], v238, s[4:5]
	global_load_dwordx4 v[132:135], v238, s[4:5] offset:16
	global_load_dwordx4 v[136:139], v239, s[6:7]
	global_load_dwordx4 v[140:143], v239, s[6:7] offset:16
	s_mov_b32 s21, 1
	s_lshl_b32 s28, s15, 8
	s_add_i32 s28, s28, 0x4000
	s_lshl_b32 s29, s21, 6
	s_add_i32 s28, s28, s29
	s_add_i32 s29, s21, s17
	s_add_i32 s29, s29, -4
	s_lshl_b32 s29, s29, 6
	s_lshl_b32 s26, s15, 12
	s_add_i32 s29, s29, s26
	s_cmp_lt_u32 s21, 4
	s_cselect_b32 s28, s28, s29
	s_lshl_b32 s26, s28, 13
	s_lshl_b32 s29, s14, 8
	s_add_i32 s26, s26, s29
	s_add_i32 s26, s26, 0x1000
	s_lshl_b32 s27, s28, 1
	s_mul_i32 s29, s14, 0x440000
	s_add_i32 s27, s27, s29
	v_add_u32_e32 v238, s26, v163
	v_add_u32_e32 v239, s27, v165
	global_load_dwordx4 v[202:205], v238, s[4:5]
	global_load_dwordx4 v[206:209], v238, s[4:5] offset:16
	global_load_dwordx4 v[210:213], v239, s[6:7]
	global_load_dwordx4 v[214:217], v239, s[6:7] offset:16
	s_lshl_b32 s0, s15, 12
	s_lshl_b32 s1, s19, 6
	s_add_i32 s0, s0, s1
	s_add_i32 s0, s0, s12
	v_and_b32_e32 v232, 15, v162
	v_bfe_u32 v233, v162, 4, 2
	v_add_u32_e32 v232, s0, v232
	v_lshlrev_b32_e32 v232, 13, v232
	v_lshl_add_u32 v232, v233, 4, v232
	s_lshl_b32 s1, s14, 8
	v_add_u32_e32 v232, s1, v232
	v_add_u32_e32 v233, 0x20000, v232
	global_load_dwordx4 v[0:3], v232, s[4:5] offset:0
	global_load_dwordx4 v[4:7], v232, s[4:5] offset:64
	global_load_dwordx4 v[8:11], v232, s[4:5] offset:128
	global_load_dwordx4 v[12:15], v232, s[4:5] offset:192
	global_load_dwordx4 v[16:19], v233, s[4:5] offset:0
	global_load_dwordx4 v[20:23], v233, s[4:5] offset:64
	global_load_dwordx4 v[24:27], v233, s[4:5] offset:128
	global_load_dwordx4 v[28:31], v233, s[4:5] offset:192
	s_mov_b32 s21, 2
	s_lshl_b32 s28, s15, 8
	s_add_i32 s28, s28, 0x4000
	s_lshl_b32 s29, s21, 6
	s_add_i32 s28, s28, s29
	s_add_i32 s29, s21, s17
	s_add_i32 s29, s29, -4
	s_lshl_b32 s29, s29, 6
	s_lshl_b32 s26, s15, 12
	s_add_i32 s29, s29, s26
	s_cmp_lt_u32 s21, 4
	s_cselect_b32 s28, s28, s29
	s_lshl_b32 s26, s28, 13
	s_lshl_b32 s29, s14, 8
	s_add_i32 s26, s26, s29
	s_add_i32 s26, s26, 0x1000
	s_lshl_b32 s27, s28, 1
	s_mul_i32 s29, s14, 0x440000
	s_add_i32 s27, s27, s29
	v_add_u32_e32 v238, s26, v163
	v_add_u32_e32 v239, s27, v165
	global_load_dwordx4 v[170:173], v238, s[4:5]
	global_load_dwordx4 v[174:177], v238, s[4:5] offset:16
	global_load_dwordx4 v[178:181], v239, s[6:7]
	global_load_dwordx4 v[182:185], v239, s[6:7] offset:16
	v_mov_b32_e32 v32, 0
	v_mov_b32_e32 v33, 0
	v_mov_b32_e32 v34, 0
	v_mov_b32_e32 v35, 0
	v_mov_b32_e32 v36, 0
	v_mov_b32_e32 v37, 0
	v_mov_b32_e32 v38, 0
	v_mov_b32_e32 v39, 0
	v_mov_b32_e32 v40, 0
	v_mov_b32_e32 v41, 0
	v_mov_b32_e32 v42, 0
	v_mov_b32_e32 v43, 0
	v_mov_b32_e32 v44, 0
	v_mov_b32_e32 v45, 0
	v_mov_b32_e32 v46, 0
	v_mov_b32_e32 v47, 0
	v_mov_b32_e32 v48, 0
	v_mov_b32_e32 v49, 0
	v_mov_b32_e32 v50, 0
	v_mov_b32_e32 v51, 0
	v_mov_b32_e32 v52, 0
	v_mov_b32_e32 v53, 0
	v_mov_b32_e32 v54, 0
	v_mov_b32_e32 v55, 0
	v_mov_b32_e32 v56, 0
	v_mov_b32_e32 v57, 0
	v_mov_b32_e32 v58, 0
	v_mov_b32_e32 v59, 0
	v_mov_b32_e32 v60, 0
	v_mov_b32_e32 v61, 0
	v_mov_b32_e32 v62, 0
	v_mov_b32_e32 v63, 0
	v_mov_b32_e32 v64, 0
	v_mov_b32_e32 v65, 0
	v_mov_b32_e32 v66, 0
	v_mov_b32_e32 v67, 0
	v_mov_b32_e32 v68, 0
	v_mov_b32_e32 v69, 0
	v_mov_b32_e32 v70, 0
	v_mov_b32_e32 v71, 0
	v_mov_b32_e32 v72, 0
	v_mov_b32_e32 v73, 0
	v_mov_b32_e32 v74, 0
	v_mov_b32_e32 v75, 0
	v_mov_b32_e32 v76, 0
	v_mov_b32_e32 v77, 0
	v_mov_b32_e32 v78, 0
	v_mov_b32_e32 v79, 0
	v_mov_b32_e32 v80, 0
	v_mov_b32_e32 v81, 0
	v_mov_b32_e32 v82, 0
	v_mov_b32_e32 v83, 0
	v_mov_b32_e32 v84, 0
	v_mov_b32_e32 v85, 0
	v_mov_b32_e32 v86, 0
	v_mov_b32_e32 v87, 0
	v_mov_b32_e32 v88, 0
	v_mov_b32_e32 v89, 0
	v_mov_b32_e32 v90, 0
	v_mov_b32_e32 v91, 0
	v_mov_b32_e32 v92, 0
	v_mov_b32_e32 v93, 0
	v_mov_b32_e32 v94, 0
	v_mov_b32_e32 v95, 0
	v_mov_b32_e32 v222, 0xf149f2ca
	v_mov_b32_e32 v224, 0
	v_mov_b32_e32 v226, 0x7149f2ca
	v_mov_b32_e32 v223, 0xf149f2ca
	v_mov_b32_e32 v225, 0
	v_mov_b32_e32 v227, 0x7149f2ca
	s_movk_i32 s0, 0x1d1
	v_cmp_gt_u32_e32 vcc, s0, v162
	v_lshlrev_b32_e32 v235, 2, v162
	v_add_u32_e32 v235, 110848, v235
	s_waitcnt vmcnt(20)
	s_and_saveexec_b64 s[2:3], vcc
	v_mul_f32_e32 v234, 0x413504f3, v234
	ds_write_b32 v235, v234
	s_mov_b64 exec, s[2:3]
	s_waitcnt vmcnt(16)
	ds_write_b128 v164, v[128:131]
	ds_write_b128 v164, v[132:135] offset:16
	ds_write_b128 v166, v[136:139]
	ds_write_b128 v166, v[140:143] offset:16
	s_waitcnt lgkmcnt(0)
	s_barrier
	s_mov_b32 s21, 0
	s_mov_b32 s65, 0
	s_mov_b32 s66, 1
	s_cmp_lt_u32 s10, 4
	s_cbranch_scc1 .Lna_tile
	s_barrier
.Lna_tile:
	s_add_i32 s22, s21, 1
	s_cmp_ge_u32 s22, s18
	s_cbranch_scc1 .Lna_noload
	s_mul_i32 s24, s66, 18432
	s_mul_i32 s23, s66, 17408
	v_add_u32_e32 v236, s23, v164
	v_add_u32_e32 v237, s24, v166
	s_add_i32 s23, s21, 2
	s_cmp_ge_u32 s23, s18
	s_cbranch_scc1 .Lna_w0
	s_waitcnt vmcnt(4)
	s_branch .Lna_w1

; __device__ __forceinline__ void phase_na(const Params& p, unsigned char* lds) {
;     ...
;             if (kt + 1 < ntile) { NA_WRITE(ra, (kt + 1) & 1); if (kt + 2 < ntile) NA_LOAD(ra, kt + 2); }
;             const bool band = kt >= 4; const int kr = rs_lo + kt - 4;
;             if (!(band && (kr < rsq || kr >= rsq + 8))) {
;                 const bf16_t* Kt = KtB + (kt & 1) * (64 * 136); const bf16_t* vt = vtB + (kt & 1) * (128 * 72);
;                 f32x4 st[2][4];
;                 const int wlo0 = min(max(qc0 - 8, 0), 48), whi0 = min(max(qc0 + 7, 0), 48) + 16, wlo1 = min(max(qc0 + 8, 0), 48), whi1 = min(max(qc0 + 23, 0), 48) + 16;
; #pragma unroll
;                 for (int nt = 0; nt < 4; ++nt) {
;                     const bool act0 = !band || (16 * nt < whi0 && 16 * nt + 16 > wlo0), act1 = !band || (16 * nt < whi1 && 16 * nt + 16 > wlo1);
;                     st[0][nt] = (f32x4){0.f, 0.f, 0.f, 0.f}; st[1][nt] = (f32x4){0.f, 0.f, 0.f, 0.f};
;                     if (act0 || act1) {
;                         bf16x8 Bk[4];
; #pragma unroll
;                         for (int ks = 0; ks < 4; ++ks) Bk[ks] = *(const bf16x8*)(Kt + (nt * 16 + fr) * 136 + ks * 32 + fq * 8);
; #pragma unroll
;                         for (int ks = 0; ks < 4; ++ks) {
;                             if (act0) st[0][nt] = __builtin_amdgcn_mfma_f32_16x16x32_bf16(Bk[ks], aq[0][ks], st[0][nt], 0, 0, 0);
;                             if (act1) st[1][nt] = __builtin_amdgcn_mfma_f32_16x16x32_bf16(Bk[ks], aq[1][ks], st[1][nt], 0, 0, 0); }
;                     }
;                 }
;                 unsigned pk[2][4][2];
; #pragma unroll
;                 for (int mt = 0; mt < 2; ++mt) {
;                     __builtin_amdgcn_sched_barrier(0);
;                     const int c = qc0 + 16 * mt + fr; const int cs = min(max(c - 8, 0), 48); const int wlo = mt ? wlo1 : wlo0, whi = mt ? whi1 : whi0;
;                     float mx = -1e30f;
; #pragma unroll
;                     for (int nt = 0; nt < 4; ++nt) {
;                         const bool act = !band || (16 * nt < whi && 16 * nt + 16 > wlo);
;                         if (act) {
; #pragma unroll
;                             for (int j = 0; j < 4; ++j) { float v = st[mt][nt][j] * scale;
.Lna_w1:
	s_bitcmp1_b32 s22, 0
	s_cbranch_scc1 .Lna_setB
	ds_write_b128 v236, v[170:173]
	ds_write_b128 v236, v[174:177] offset:16
	ds_write_b128 v237, v[178:181]
	ds_write_b128 v237, v[182:185] offset:16
	s_add_i32 s22, s21, 3
	s_cmp_ge_u32 s22, s18
	s_cbranch_scc1 .Lna_noload
	s_lshl_b32 s28, s15, 8
	s_add_i32 s28, s28, 0x4000
	s_lshl_b32 s29, s22, 6
	s_add_i32 s28, s28, s29
	s_add_i32 s29, s22, s17
	s_add_i32 s29, s29, -4
	s_lshl_b32 s29, s29, 6
	s_lshl_b32 s26, s15, 12
	s_add_i32 s29, s29, s26
	s_cmp_lt_u32 s22, 4
	s_cselect_b32 s28, s28, s29
	s_lshl_b32 s26, s28, 13
	s_lshl_b32 s29, s14, 8
	s_add_i32 s26, s26, s29
	s_add_i32 s26, s26, 0x1000
	s_lshl_b32 s27, s28, 1
	s_mul_i32 s29, s14, 0x440000
	s_add_i32 s27, s27, s29
	v_add_u32_e32 v238, s26, v163
	v_add_u32_e32 v239, s27, v165
	global_load_dwordx4 v[170:173], v238, s[4:5]
	global_load_dwordx4 v[174:177], v238, s[4:5] offset:16
	global_load_dwordx4 v[178:181], v239, s[6:7]
	global_load_dwordx4 v[182:185], v239, s[6:7] offset:16
	s_branch .Lna_noload
.Lna_setB:
	ds_write_b128 v236, v[202:205]
	ds_write_b128 v236, v[206:209] offset:16
	ds_write_b128 v237, v[210:213]
	ds_write_b128 v237, v[214:217] offset:16
	s_add_i32 s22, s21, 3
	s_cmp_ge_u32 s22, s18
	s_cbranch_scc1 .Lna_noload
	s_lshl_b32 s28, s15, 8
	s_add_i32 s28, s28, 0x4000
	s_lshl_b32 s29, s22, 6
	s_add_i32 s28, s28, s29
	s_add_i32 s29, s22, s17
	s_add_i32 s29, s29, -4
	s_lshl_b32 s29, s29, 6
	s_lshl_b32 s26, s15, 12
	s_add_i32 s29, s29, s26
	s_cmp_lt_u32 s22, 4
	s_cselect_b32 s28, s28, s29
	s_lshl_b32 s26, s28, 13
	s_lshl_b32 s29, s14, 8
	s_add_i32 s26, s26, s29
	s_add_i32 s26, s26, 0x1000
	s_lshl_b32 s27, s28, 1
	s_mul_i32 s29, s14, 0x440000
	s_add_i32 s27, s27, s29
	v_add_u32_e32 v238, s26, v163
	v_add_u32_e32 v239, s27, v165
	global_load_dwordx4 v[202:205], v238, s[4:5]
	global_load_dwordx4 v[206:209], v238, s[4:5] offset:16
	global_load_dwordx4 v[210:213], v239, s[6:7]
	global_load_dwordx4 v[214:217], v239, s[6:7] offset:16
.Lna_noload:
	s_mov_b32 s64, 0
	s_add_i32 s25, s17, s21
	s_add_i32 s25, s25, -4
	s_sub_i32 s22, s25, s20
	s_cmp_lt_u32 s21, 4
	s_cbranch_scc1 .Lna_ctx
	s_cmp_lt_u32 s22, 8
	s_cbranch_scc0 .Lna_p1_end
	s_sub_i32 s22, s25, s19
	s_add_i32 s22, s22, 7
	s_mul_i32 s22, s22, 0x7c
	v_add_u32_e32 v230, s22, v220
	v_add_u32_e32 v231, s22, v221
	ds_read2_b32 v[96:97], v230 offset0:0 offset1:1
	ds_read2_b32 v[98:99], v230 offset0:2 offset1:3
	ds_read2_b32 v[100:101], v230 offset0:16 offset1:17
	ds_read2_b32 v[102:103], v230 offset0:18 offset1:19
	ds_read2_b32 v[104:105], v230 offset0:32 offset1:33
	ds_read2_b32 v[106:107], v230 offset0:34 offset1:35
	ds_read2_b32 v[108:109], v230 offset0:48 offset1:49
	ds_read2_b32 v[110:111], v230 offset0:50 offset1:51
	ds_read2_b32 v[112:113], v231 offset0:0 offset1:1
	ds_read2_b32 v[114:115], v231 offset0:2 offset1:3
	ds_read2_b32 v[116:117], v231 offset0:16 offset1:17
	ds_read2_b32 v[118:119], v231 offset0:18 offset1:19
	ds_read2_b32 v[120:121], v231 offset0:32 offset1:33
	ds_read2_b32 v[122:123], v231 offset0:34 offset1:35
	ds_read2_b32 v[124:125], v231 offset0:48 offset1:49
	ds_read2_b32 v[126:127], v231 offset0:50 offset1:51
	s_mul_i32 s24, s65, 18432
	s_mul_i32 s23, s65, 17408
	v_add_u32_e32 v228, s23, v167
	v_add_u32_e32 v229, s24, v168
	ds_read_b128 v[128:131], v228 offset:0
	ds_read_b128 v[132:135], v228 offset:64
	ds_read_b128 v[136:139], v228 offset:128
	ds_read_b128 v[140:143], v228 offset:192
	s_waitcnt lgkmcnt(4)
	v_mov_b32_e32 v232, 0xf149f2ca
	v_add_f32_e32 v96, v96, v186
	v_add_f32_e32 v97, v97, v187
	v_add_f32_e32 v98, v98, v188
	v_add_f32_e32 v99, v99, v189
	v_add_f32_e32 v100, v100, v190
	v_add_f32_e32 v101, v101, v191
	v_add_f32_e32 v102, v102, v192
	v_add_f32_e32 v103, v103, v193
	v_add_f32_e32 v104, v104, v194
	v_add_f32_e32 v105, v105, v195
	v_add_f32_e32 v106, v106, v196
	v_add_f32_e32 v107, v107, v197
	v_add_f32_e32 v108, v108, v198
	v_add_f32_e32 v109, v109, v199
	v_add_f32_e32 v110, v110, v200
	v_add_f32_e32 v111, v111, v201
	v_cndmask_b32_e64 v112, v232, v112, s[32:33]
	v_cndmask_b32_e64 v113, v232, v113, s[34:35]
	v_cndmask_b32_e64 v114, v232, v114, s[36:37]
	v_cndmask_b32_e64 v115, v232, v115, s[38:39]
	v_cndmask_b32_e64 v116, v232, v116, s[40:41]
	v_cndmask_b32_e64 v117, v232, v117, s[42:43]
	v_cndmask_b32_e64 v118, v232, v118, s[44:45]
	v_cndmask_b32_e64 v119, v232, v119, s[46:47]
	v_cndmask_b32_e64 v120, v232, v120, s[48:49]
	v_cndmask_b32_e64 v121, v232, v121, s[50:51]
	v_cndmask_b32_e64 v122, v232, v122, s[52:53]
	v_cndmask_b32_e64 v123, v232, v123, s[54:55]
	v_cndmask_b32_e64 v124, v232, v124, s[56:57]
	v_cndmask_b32_e64 v125, v232, v125, s[58:59]
	v_cndmask_b32_e64 v126, v232, v126, s[60:61]
	v_cndmask_b32_e64 v127, v232, v127, s[62:63]
	s_branch .Lna_qk
.Lna_ctx:
	s_mul_i32 s24, s65, 18432
	s_mul_i32 s23, s65, 17408
	v_add_u32_e32 v228, s23, v167
	v_add_u32_e32 v229, s24, v168
	ds_read_b128 v[128:131], v228 offset:0
	ds_read_b128 v[132:135], v228 offset:64
	ds_read_b128 v[136:139], v228 offset:128
	ds_read_b128 v[140:143], v228 offset:192
	v_mov_b32_e32 v96, 0
	v_mov_b32_e32 v97, 0
	v_mov_b32_e32 v98, 0
	v_mov_b32_e32 v99, 0
	v_mov_b32_e32 v100, 0
	v_mov_b32_e32 v101, 0
	v_mov_b32_e32 v102, 0
	v_mov_b32_e32 v103, 0
	v_mov_b32_e32 v104, 0
	v_mov_b32_e32 v105, 0
	v_mov_b32_e32 v106, 0
	v_mov_b32_e32 v107, 0
	v_mov_b32_e32 v108, 0
	v_mov_b32_e32 v109, 0
	v_mov_b32_e32 v110, 0
	v_mov_b32_e32 v111, 0
	v_mov_b32_e32 v112, 0
	v_mov_b32_e32 v113, 0
	v_mov_b32_e32 v114, 0
	v_mov_b32_e32 v115, 0
	v_mov_b32_e32 v116, 0
	v_mov_b32_e32 v117, 0
	v_mov_b32_e32 v118, 0
	v_mov_b32_e32 v119, 0
	v_mov_b32_e32 v120, 0
	v_mov_b32_e32 v121, 0
	v_mov_b32_e32 v122, 0
	v_mov_b32_e32 v123, 0
	v_mov_b32_e32 v124, 0
	v_mov_b32_e32 v125, 0
	v_mov_b32_e32 v126, 0
	v_mov_b32_e32 v127, 0
; __device__ __forceinline__ void phase_na(const Params& p, unsigned char* lds) {
;     ...
;             if (!(band && (kr < rsq || kr >= rsq + 8))) {
;                 const bf16_t* Kt = KtB + (kt & 1) * (64 * 136); const bf16_t* vt = vtB + (kt & 1) * (128 * 72);
;                 f32x4 st[2][4];
;                 const int wlo0 = min(max(qc0 - 8, 0), 48), whi0 = min(max(qc0 + 7, 0), 48) + 16, wlo1 = min(max(qc0 + 8, 0), 48), whi1 = min(max(qc0 + 23, 0), 48) + 16;
; #pragma unroll
;                 for (int nt = 0; nt < 4; ++nt) {
;                     const bool act0 = !band || (16 * nt < whi0 && 16 * nt + 16 > wlo0), act1 = !band || (16 * nt < whi1 && 16 * nt + 16 > wlo1);
;                     st[0][nt] = (f32x4){0.f, 0.f, 0.f, 0.f}; st[1][nt] = (f32x4){0.f, 0.f, 0.f, 0.f};
;                     if (act0 || act1) {
;                         bf16x8 Bk[4];
; #pragma unroll
;                         for (int ks = 0; ks < 4; ++ks) Bk[ks] = *(const bf16x8*)(Kt + (nt * 16 + fr) * 136 + ks * 32 + fq * 8);
; #pragma unroll
;                         for (int ks = 0; ks < 4; ++ks) {
;                             if (act0) st[0][nt] = __builtin_amdgcn_mfma_f32_16x16x32_bf16(Bk[ks], aq[0][ks], st[0][nt], 0, 0, 0);
;                             if (act1) st[1][nt] = __builtin_amdgcn_mfma_f32_16x16x32_bf16(Bk[ks], aq[1][ks], st[1][nt], 0, 0, 0); }
;                     }
;                 }
;                 unsigned pk[2][4][2];
; #pragma unroll
;                 for (int mt = 0; mt < 2; ++mt) {
;                     __builtin_amdgcn_sched_barrier(0);
;                     const int c = qc0 + 16 * mt + fr; const int cs = min(max(c - 8, 0), 48); const int wlo = mt ? wlo1 : wlo0, whi = mt ? whi1 : whi0;
;                     float mx = -1e30f;
; #pragma unroll
;                     for (int nt = 0; nt < 4; ++nt) {
;                         const bool act = !band || (16 * nt < whi && 16 * nt + 16 > wlo);
;                         if (act) {
; #pragma unroll
;                             for (int j = 0; j < 4; ++j) { float v = st[mt][nt][j] * scale;
;                                 if (band) { const int kc = nt * 16 + fq * 4 + j; const bool valid = kc >= cs && kc < cs + 16; const int dci = min(max(kc - c + 15, 0), 30);
;                                     v += rbt[(kr - qr + 7) * 31 + dci]; v = valid ? v : -1e30f; }
.Lna_qk:
	s_mov_b32 s64, 1
	ds_read_b128 v[144:147], v228 offset:4352
	ds_read_b128 v[148:151], v228 offset:4416
	ds_read_b128 v[152:155], v228 offset:4480
	ds_read_b128 v[156:159], v228 offset:4544
	s_waitcnt lgkmcnt(4)
	v_mfma_f32_16x16x32_bf16 v[96:99], v[128:131], v[0:3], v[96:99]
	v_mfma_f32_16x16x32_bf16 v[112:115], v[128:131], v[16:19], v[112:115]
	v_mfma_f32_16x16x32_bf16 v[96:99], v[132:135], v[4:7], v[96:99]
	v_mfma_f32_16x16x32_bf16 v[112:115], v[132:135], v[20:23], v[112:115]
	v_mfma_f32_16x16x32_bf16 v[96:99], v[136:139], v[8:11], v[96:99]
	v_mfma_f32_16x16x32_bf16 v[112:115], v[136:139], v[24:27], v[112:115]
	v_mfma_f32_16x16x32_bf16 v[96:99], v[140:143], v[12:15], v[96:99]
	v_mfma_f32_16x16x32_bf16 v[112:115], v[140:143], v[28:31], v[112:115]
	ds_read_b128 v[128:131], v228 offset:8704
	ds_read_b128 v[132:135], v228 offset:8768
	ds_read_b128 v[136:139], v228 offset:8832
	ds_read_b128 v[140:143], v228 offset:8896
	s_waitcnt lgkmcnt(4)
	v_mfma_f32_16x16x32_bf16 v[100:103], v[144:147], v[0:3], v[100:103]
	v_mfma_f32_16x16x32_bf16 v[116:119], v[144:147], v[16:19], v[116:119]
	v_mfma_f32_16x16x32_bf16 v[100:103], v[148:151], v[4:7], v[100:103]
	v_mfma_f32_16x16x32_bf16 v[116:119], v[148:151], v[20:23], v[116:119]
	v_mfma_f32_16x16x32_bf16 v[100:103], v[152:155], v[8:11], v[100:103]
	v_mfma_f32_16x16x32_bf16 v[116:119], v[152:155], v[24:27], v[116:119]
	v_mfma_f32_16x16x32_bf16 v[100:103], v[156:159], v[12:15], v[100:103]
	v_mfma_f32_16x16x32_bf16 v[116:119], v[156:159], v[28:31], v[116:119]
	ds_read_b128 v[144:147], v228 offset:13056
	ds_read_b128 v[148:151], v228 offset:13120
	ds_read_b128 v[152:155], v228 offset:13184
	ds_read_b128 v[156:159], v228 offset:13248
	s_waitcnt lgkmcnt(4)
	v_mfma_f32_16x16x32_bf16 v[104:107], v[128:131], v[0:3], v[104:107]
	v_mfma_f32_16x16x32_bf16 v[120:123], v[128:131], v[16:19], v[120:123]
	v_mfma_f32_16x16x32_bf16 v[104:107], v[132:135], v[4:7], v[104:107]
	v_mfma_f32_16x16x32_bf16 v[120:123], v[132:135], v[20:23], v[120:123]
	v_mfma_f32_16x16x32_bf16 v[104:107], v[136:139], v[8:11], v[104:107]
	v_mfma_f32_16x16x32_bf16 v[120:123], v[136:139], v[24:27], v[120:123]
	v_mfma_f32_16x16x32_bf16 v[104:107], v[140:143], v[12:15], v[104:107]
	v_mfma_f32_16x16x32_bf16 v[120:123], v[140:143], v[28:31], v[120:123]
	s_waitcnt lgkmcnt(0)
	v_mfma_f32_16x16x32_bf16 v[108:111], v[144:147], v[0:3], v[108:111]
	v_mfma_f32_16x16x32_bf16 v[124:127], v[144:147], v[16:19], v[124:127]
	v_mfma_f32_16x16x32_bf16 v[108:111], v[148:151], v[4:7], v[108:111]
	v_mfma_f32_16x16x32_bf16 v[124:127], v[148:151], v[20:23], v[124:127]
	v_mfma_f32_16x16x32_bf16 v[108:111], v[152:155], v[8:11], v[108:111]
	v_mfma_f32_16x16x32_bf16 v[124:127], v[152:155], v[24:27], v[124:127]
	v_mfma_f32_16x16x32_bf16 v[108:111], v[156:159], v[12:15], v[108:111]
	v_mfma_f32_16x16x32_bf16 v[124:127], v[156:159], v[28:31], v[124:127]
	ds_read_b64 v[128:129], v229 offset:0
	ds_read_b64 v[130:131], v229 offset:32
	ds_read_b64 v[132:133], v229 offset:2304
	ds_read_b64 v[134:135], v229 offset:2336
	ds_read_b64 v[136:137], v229 offset:4608
	ds_read_b64 v[138:139], v229 offset:4640
	ds_read_b64 v[140:141], v229 offset:6912
	ds_read_b64 v[142:143], v229 offset:6944
	ds_read_b64 v[144:145], v229 offset:9216
	ds_read_b64 v[146:147], v229 offset:9248
	ds_read_b64 v[148:149], v229 offset:11520
	ds_read_b64 v[150:151], v229 offset:11552
	ds_read_b64 v[152:153], v229 offset:13824
	ds_read_b64 v[154:155], v229 offset:13856
	ds_read_b64 v[156:157], v229 offset:16128
	ds_read_b64 v[158:159], v229 offset:16160
	v_max3_f32 v232, v96, v97, v98
	v_max3_f32 v234, v99, v100, v101
	v_max3_f32 v236, v102, v103, v104
	v_max3_f32 v232, v232, v105, v106
	v_max3_f32 v234, v234, v107, v108
	v_max3_f32 v236, v236, v109, v110
	v_max3_f32 v232, v232, v234, v111
	v_max_f32_e32 v232, v232, v236
	v_max3_f32 v233, v112, v113, v114
	v_max3_f32 v235, v115, v116, v117
	v_max3_f32 v237, v118, v119, v120
	v_max3_f32 v233, v233, v121, v122
	v_max3_f32 v235, v235, v123, v124
	v_max3_f32 v237, v237, v125, v126
	v_max3_f32 v233, v233, v235, v127
	v_max_f32_e32 v233, v233, v237
	ds_bpermute_b32 v234, v218, v232
	ds_bpermute_b32 v235, v218, v233
	s_waitcnt lgkmcnt(0)
	v_max_f32_e32 v232, v232, v234
	v_max_f32_e32 v233, v233, v235
	ds_bpermute_b32 v234, v219, v232
	ds_bpermute_b32 v235, v219, v233
.Lna_p1_end:
	s_waitcnt lgkmcnt(0)
	s_barrier
	s_cmp_eq_u32 s64, 0
	s_cbranch_scc1 .Lna_p2_end
	v_max_f32_e32 v232, v232, v234
	v_max_f32_e32 v233, v233, v235
	v_mul_f32_e32 v232, s30, v232
	v_mul_f32_e32 v233, s30, v233
	v_sub_f32_e32 v236, v232, v222
	v_cmp_lt_f32_e32 vcc, 0x41000000, v236
	s_cbranch_vccz .Lna_fast0
	v_max_f32_e32 v236, v222, v232
	v_sub_f32_e32 v237, v222, v236
	v_exp_f32_e32 v237, v237
	v_mov_b32_e32 v222, v236
	v_sub_f32_e32 v226, 0, v236
	v_mul_f32_e32 v224, v224, v237
	v_mul_f32_e32 v32, v32, v237
	v_mul_f32_e32 v33, v33, v237
	v_mul_f32_e32 v34, v34, v237
	v_mul_f32_e32 v35, v35, v237
	v_mul_f32_e32 v36, v36, v237
	v_mul_f32_e32 v37, v37, v237
	v_mul_f32_e32 v38, v38, v237
	v_mul_f32_e32 v39, v39, v237
	v_mul_f32_e32 v40, v40, v237
	v_mul_f32_e32 v41, v41, v237
	v_mul_f32_e32 v42, v42, v237
	v_mul_f32_e32 v43, v43, v237
	v_mul_f32_e32 v44, v44, v237
	v_mul_f32_e32 v45, v45, v237
	v_mul_f32_e32 v46, v46, v237
	v_mul_f32_e32 v47, v47, v237
	v_mul_f32_e32 v48, v48, v237
	v_mul_f32_e32 v49, v49, v237
	v_mul_f32_e32 v50, v50, v237
	v_mul_f32_e32 v51, v51, v237
	v_mul_f32_e32 v52, v52, v237
	v_mul_f32_e32 v53, v53, v237
	v_mul_f32_e32 v54, v54, v237
	v_mul_f32_e32 v55, v55, v237
	v_mul_f32_e32 v56, v56, v237
	v_mul_f32_e32 v57, v57, v237
	v_mul_f32_e32 v58, v58, v237
	v_mul_f32_e32 v59, v59, v237
	v_mul_f32_e32 v60, v60, v237
	v_mul_f32_e32 v61, v61, v237
	v_mul_f32_e32 v62, v62, v237
	v_mul_f32_e32 v63, v63, v237

; __device__ __forceinline__ void phase_na(const Params& p, unsigned char* lds) {
;     ...
;                     float ls = 0.f;
; #pragma unroll
;                     for (int nt = 0; nt < 4; ++nt) {
;                         const bool act = !band || (16 * nt < whi && 16 * nt + 16 > wlo);
;                         if (act) { const float p0 = __builtin_amdgcn_exp2f(st[mt][nt][0] - mn), p1 = __builtin_amdgcn_exp2f(st[mt][nt][1] - mn), p2 = __builtin_amdgcn_exp2f(st[mt][nt][2] - mn), p3 = __builtin_amdgcn_exp2f(st[mt][nt][3] - mn);
;                             ls += (p0 + p1) + (p2 + p3); pk[mt][nt][0] = pk2(p0, p1); pk[mt][nt][1] = pk2(p2, p3); }
;                         else { pk[mt][nt][0] = 0u; pk[mt][nt][1] = 0u; }
;                     }
;                     lrow[mt] = lrow[mt] * alpha + ls;
;                     if (resc) {
; #pragma unroll
;                         for (int dt = 0; dt < 8; ++dt) Oa[mt][dt] = Oa[mt][dt] * alpha; }
;                 }
;                 __builtin_amdgcn_sched_barrier(0);
; #pragma unroll
;                 for (int kk = 0; kk < 2; ++kk) {
;                     const int ta = 2 * kk, tb = 2 * kk + 1;
;                     const bf16x8 Bp0 = as_bf16x8((u32x4){pk[0][ta][0], pk[0][ta][1], pk[0][tb][0], pk[0][tb][1]}), Bp1 = as_bf16x8((u32x4){pk[1][ta][0], pk[1][ta][1], pk[1][tb][0], pk[1][tb][1]});
; #pragma unroll
;                     for (int dt = 0; dt < 8; ++dt) {
;                         const u32x2 va = *(const u32x2*)(vt + (dt * 16 + fr) * 72 + 16 * ta + fq * 4), vb = *(const u32x2*)(vt + (dt * 16 + fr) * 72 + 16 * tb + fq * 4);
;                         const bf16x8 Av = as_bf16x8((u32x4){va.x, va.y, vb.x, vb.y});
;                         Oa[0][dt] = __builtin_amdgcn_mfma_f32_16x16x32_bf16(Av, Bp0, Oa[0][dt], 0, 0, 0);
;                         Oa[1][dt] = __builtin_amdgcn_mfma_f32_16x16x32_bf16(Av, Bp1, Oa[1][dt], 0, 0, 0); }
;                     __builtin_amdgcn_sched_group_barrier(0x100, 8, 0);
; #pragma unroll
;                     for (int q = 0; q < 4; ++q) { __builtin_amdgcn_sched_group_barrier(0x008, 2, 0); __builtin_amdgcn_sched_group_barrier(0x100, 2, 0); }
;                     __builtin_amdgcn_sched_group_barrier(0x008, 8, 0);
;                     __builtin_amdgcn_sched_barrier(0);
;                 }
.Lna_fast1:
	v_fma_f32 v96, v96, s30, v226
	v_fma_f32 v97, v97, s30, v226
	v_fma_f32 v98, v98, s30, v226
	v_fma_f32 v99, v99, s30, v226
	v_fma_f32 v100, v100, s30, v226
	v_fma_f32 v101, v101, s30, v226
	v_fma_f32 v102, v102, s30, v226
	v_fma_f32 v103, v103, s30, v226
	v_fma_f32 v104, v104, s30, v226
	v_fma_f32 v105, v105, s30, v226
	v_fma_f32 v106, v106, s30, v226
	v_fma_f32 v107, v107, s30, v226
	v_fma_f32 v108, v108, s30, v226
	v_fma_f32 v109, v109, s30, v226
	v_fma_f32 v110, v110, s30, v226
	v_fma_f32 v111, v111, s30, v226
	v_fma_f32 v112, v112, s30, v227
	v_fma_f32 v113, v113, s30, v227
	v_fma_f32 v114, v114, s30, v227
	v_fma_f32 v115, v115, s30, v227
	v_fma_f32 v116, v116, s30, v227
	v_fma_f32 v117, v117, s30, v227
	v_fma_f32 v118, v118, s30, v227
	v_fma_f32 v119, v119, s30, v227
	v_fma_f32 v120, v120, s30, v227
	v_fma_f32 v121, v121, s30, v227
	v_fma_f32 v122, v122, s30, v227
	v_fma_f32 v123, v123, s30, v227
	v_fma_f32 v124, v124, s30, v227
	v_fma_f32 v125, v125, s30, v227
	v_fma_f32 v126, v126, s30, v227
	v_fma_f32 v127, v127, s30, v227
	v_exp_f32_e32 v96, v96
	v_exp_f32_e32 v97, v97
	v_exp_f32_e32 v98, v98
	v_exp_f32_e32 v99, v99
	v_exp_f32_e32 v100, v100
	v_exp_f32_e32 v101, v101
	v_exp_f32_e32 v102, v102
	v_exp_f32_e32 v103, v103
	v_exp_f32_e32 v104, v104
	v_exp_f32_e32 v105, v105
	v_exp_f32_e32 v106, v106
	v_exp_f32_e32 v107, v107
	v_exp_f32_e32 v108, v108
	v_exp_f32_e32 v109, v109
	v_exp_f32_e32 v110, v110
	v_exp_f32_e32 v111, v111
	v_exp_f32_e32 v112, v112
	v_exp_f32_e32 v113, v113
	v_exp_f32_e32 v114, v114
	v_exp_f32_e32 v115, v115
	v_exp_f32_e32 v116, v116
	v_exp_f32_e32 v117, v117
	v_exp_f32_e32 v118, v118
	v_exp_f32_e32 v119, v119
	v_exp_f32_e32 v120, v120
	v_exp_f32_e32 v121, v121
	v_exp_f32_e32 v122, v122
	v_exp_f32_e32 v123, v123
	v_exp_f32_e32 v124, v124
	v_exp_f32_e32 v125, v125
	v_exp_f32_e32 v126, v126
	v_exp_f32_e32 v127, v127
	v_add_f32_e32 v232, v96, v97
	v_add_f32_e32 v232, v232, v98
	v_add_f32_e32 v232, v232, v99
	v_add_f32_e32 v232, v232, v100
	v_add_f32_e32 v232, v232, v101
	v_add_f32_e32 v232, v232, v102
	v_add_f32_e32 v232, v232, v103
	v_add_f32_e32 v232, v232, v104
	v_add_f32_e32 v232, v232, v105
	v_add_f32_e32 v232, v232, v106
	v_add_f32_e32 v232, v232, v107
	v_add_f32_e32 v232, v232, v108
	v_add_f32_e32 v232, v232, v109
	v_add_f32_e32 v232, v232, v110
	v_add_f32_e32 v232, v232, v111
	v_add_f32_e32 v224, v224, v232
	v_add_f32_e32 v233, v112, v113
	v_add_f32_e32 v233, v233, v114
	v_add_f32_e32 v233, v233, v115
	v_add_f32_e32 v233, v233, v116
	v_add_f32_e32 v233, v233, v117
	v_add_f32_e32 v233, v233, v118
	v_add_f32_e32 v233, v233, v119
	v_add_f32_e32 v233, v233, v120
	v_add_f32_e32 v233, v233, v121
	v_add_f32_e32 v233, v233, v122
	v_add_f32_e32 v233, v233, v123
	v_add_f32_e32 v233, v233, v124
	v_add_f32_e32 v233, v233, v125
	v_add_f32_e32 v233, v233, v126
	v_add_f32_e32 v233, v233, v127
	v_add_f32_e32 v225, v225, v233
	v_cvt_pk_bf16_f32 v96, v96, v97
	v_cvt_pk_bf16_f32 v97, v98, v99
	v_cvt_pk_bf16_f32 v98, v100, v101
	v_cvt_pk_bf16_f32 v99, v102, v103
	v_cvt_pk_bf16_f32 v104, v104, v105
	v_cvt_pk_bf16_f32 v105, v106, v107
	v_cvt_pk_bf16_f32 v106, v108, v109
	v_cvt_pk_bf16_f32 v107, v110, v111
	v_cvt_pk_bf16_f32 v112, v112, v113
	v_cvt_pk_bf16_f32 v113, v114, v115
	v_cvt_pk_bf16_f32 v114, v116, v117
	v_cvt_pk_bf16_f32 v115, v118, v119
	v_cvt_pk_bf16_f32 v120, v120, v121
	v_cvt_pk_bf16_f32 v121, v122, v123
	v_cvt_pk_bf16_f32 v122, v124, v125
	v_cvt_pk_bf16_f32 v123, v126, v127
	s_nop 1
	v_mfma_f32_16x16x32_bf16 v[32:35], v[128:131], v[96:99], v[32:35]
	v_mfma_f32_16x16x32_bf16 v[64:67], v[128:131], v[112:115], v[64:67]
	v_mfma_f32_16x16x32_bf16 v[36:39], v[132:135], v[96:99], v[36:39]
	v_mfma_f32_16x16x32_bf16 v[68:71], v[132:135], v[112:115], v[68:71]
	v_mfma_f32_16x16x32_bf16 v[40:43], v[136:139], v[96:99], v[40:43]
	v_mfma_f32_16x16x32_bf16 v[72:75], v[136:139], v[112:115], v[72:75]
	v_mfma_f32_16x16x32_bf16 v[44:47], v[140:143], v[96:99], v[44:47]
	v_mfma_f32_16x16x32_bf16 v[76:79], v[140:143], v[112:115], v[76:79]
	ds_read_b64 v[128:129], v229 offset:64
	ds_read_b64 v[130:131], v229 offset:96
	ds_read_b64 v[132:133], v229 offset:2368
	ds_read_b64 v[134:135], v229 offset:2400
	ds_read_b64 v[136:137], v229 offset:4672
	ds_read_b64 v[138:139], v229 offset:4704
	ds_read_b64 v[140:141], v229 offset:6976
	ds_read_b64 v[142:143], v229 offset:7008
	v_mfma_f32_16x16x32_bf16 v[48:51], v[144:147], v[96:99], v[48:51]
	v_mfma_f32_16x16x32_bf16 v[80:83], v[144:147], v[112:115], v[80:83]
	v_mfma_f32_16x16x32_bf16 v[52:55], v[148:151], v[96:99], v[52:55]
	v_mfma_f32_16x16x32_bf16 v[84:87], v[148:151], v[112:115], v[84:87]
	v_mfma_f32_16x16x32_bf16 v[56:59], v[152:155], v[96:99], v[56:59]
	v_mfma_f32_16x16x32_bf16 v[88:91], v[152:155], v[112:115], v[88:91]
	v_mfma_f32_16x16x32_bf16 v[60:63], v[156:159], v[96:99], v[60:63]
	v_mfma_f32_16x16x32_bf16 v[92:95], v[156:159], v[112:115], v[92:95]
	ds_read_b64 v[144:145], v229 offset:9280
	ds_read_b64 v[146:147], v229 offset:9312
	ds_read_b64 v[148:149], v229 offset:11584
	ds_read_b64 v[150:151], v229 offset:11616
	ds_read_b64 v[152:153], v229 offset:13888
	ds_read_b64 v[154:155], v229 offset:13920
	ds_read_b64 v[156:157], v229 offset:16192
	ds_read_b64 v[158:159], v229 offset:16224
	s_waitcnt lgkmcnt(8)
	v_mfma_f32_16x16x32_bf16 v[32:35], v[128:131], v[104:107], v[32:35]
	v_mfma_f32_16x16x32_bf16 v[64:67], v[128:131], v[120:123], v[64:67]
	v_mfma_f32_16x16x32_bf16 v[36:39], v[132:135], v[104:107], v[36:39]
	v_mfma_f32_16x16x32_bf16 v[68:71], v[132:135], v[120:123], v[68:71]
	v_mfma_f32_16x16x32_bf16 v[40:43], v[136:139], v[104:107], v[40:43]
	v_mfma_f32_16x16x32_bf16 v[72:75], v[136:139], v[120:123], v[72:75]
	v_mfma_f32_16x16x32_bf16 v[44:47], v[140:143], v[104:107], v[44:47]
	v_mfma_f32_16x16x32_bf16 v[76:79], v[140:143], v[120:123], v[76:79]
	s_waitcnt lgkmcnt(0)
	v_mfma_f32_16x16x32_bf16 v[48:51], v[144:147], v[104:107], v[48:51]
	v_mfma_f32_16x16x32_bf16 v[80:83], v[144:147], v[120:123], v[80:83]
	v_mfma_f32_16x16x32_bf16 v[52:55], v[148:151], v[104:107], v[52:55]
	v_mfma_f32_16x16x32_bf16 v[84:87], v[148:151], v[120:123], v[84:87]
	v_mfma_f32_16x16x32_bf16 v[56:59], v[152:155], v[104:107], v[56:59]
	v_mfma_f32_16x16x32_bf16 v[88:91], v[152:155], v[120:123], v[88:91]
	v_mfma_f32_16x16x32_bf16 v[60:63], v[156:159], v[104:107], v[60:63]
	v_mfma_f32_16x16x32_bf16 v[92:95], v[156:159], v[120:123], v[92:95]
; __device__ __forceinline__ unsigned pk2(float lo, float hi) { return __builtin_bit_cast(unsigned, __builtin_convertvector((f32x2){lo, hi}, hwbf16x2)); }
; __device__ __forceinline__ void phase_na(const Params& p, unsigned char* lds) {
;     ...
;             __syncthreads();
;         }
;         { bf16_t* ost = KtB + w * (32 * 136);
; #pragma unroll
;           for (int mt = 0; mt < 2; ++mt) {
;             float l = lrow[mt]; l += __shfl_xor(l, 16); l += __shfl_xor(l, 32); const float inv = 1.f / l;
; #pragma unroll
;             for (int dt = 0; dt < 8; ++dt) *(u32x2*)(ost + (mt * 16 + fr) * 136 + dt * 16 + fq * 4) = (u32x2){pk2(Oa[mt][dt][0] * inv, Oa[mt][dt][1] * inv), pk2(Oa[mt][dt][2] * inv, Oa[mt][dt][3] * inv)}; }
;           asm volatile("s_waitcnt lgkmcnt(0)" ::: "memory");
;           const int q = lane >> 1, hf = lane & 1;
;           bf16_t* op = O + (size_t)(b * SEQ + qr * 64 + qc0 + q) * D + h * 128 + hf * 64;
; #pragma unroll
;           for (int e = 0; e < 8; ++e) *(u32x4*)(op + e * 8) = *(const u32x4*)(ost + q * 136 + hf * 64 + e * 8); }
.Lna_p2_end:
	s_barrier
	s_mov_b32 s65, s66
	s_add_i32 s66, s66, 1
	s_cmp_eq_u32 s66, 3
	s_cselect_b32 s66, 0, s66
	s_add_i32 s21, s21, 1
	s_cmp_lt_u32 s21, s18
	s_cbranch_scc1 .Lna_tile
	s_cmp_lt_u32 s10, 4
	s_cbranch_scc0 .Lna_aligned
	s_barrier
.Lna_aligned:
	ds_bpermute_b32 v232, v218, v224
	ds_bpermute_b32 v233, v218, v225
	s_waitcnt lgkmcnt(0)
	v_add_f32_e32 v232, v232, v224
	v_add_f32_e32 v233, v233, v225
	ds_bpermute_b32 v234, v219, v232
	ds_bpermute_b32 v235, v219, v233
	s_waitcnt lgkmcnt(0)
	v_add_f32_e32 v232, v232, v234
	v_add_f32_e32 v233, v233, v235
	v_rcp_f32_e32 v234, v232
	s_nop 0
	v_fma_f32 v236, -v232, v234, 1.0
	v_fma_f32 v234, v236, v234, v234
	v_rcp_f32_e32 v235, v233
	s_nop 0
	v_fma_f32 v237, -v233, v235, 1.0
	v_fma_f32 v235, v237, v235, v235
	s_mul_i32 s0, s10, 0x2200
	v_and_b32_e32 v238, 15, v162
	v_mul_u32_u24_e32 v238, 0x110, v238
	v_bfe_u32 v239, v162, 4, 2
	v_lshl_add_u32 v238, v239, 3, v238
	v_add_u32_e32 v238, s0, v238
	v_mul_f32_e32 v32, v32, v234
	v_mul_f32_e32 v33, v33, v234
	v_mul_f32_e32 v34, v34, v234
	v_mul_f32_e32 v35, v35, v234
	v_cvt_pk_bf16_f32 v32, v32, v33
	v_cvt_pk_bf16_f32 v33, v34, v35
	ds_write_b64 v238, v[32:33] offset:0
	v_mul_f32_e32 v36, v36, v234
	v_mul_f32_e32 v37, v37, v234
	v_mul_f32_e32 v38, v38, v234
	v_mul_f32_e32 v39, v39, v234
	v_cvt_pk_bf16_f32 v36, v36, v37
	v_cvt_pk_bf16_f32 v37, v38, v39
	ds_write_b64 v238, v[36:37] offset:32
	v_mul_f32_e32 v40, v40, v234
	v_mul_f32_e32 v41, v41, v234
	v_mul_f32_e32 v42, v42, v234
	v_mul_f32_e32 v43, v43, v234
	v_cvt_pk_bf16_f32 v40, v40, v41
	v_cvt_pk_bf16_f32 v41, v42, v43
	ds_write_b64 v238, v[40:41] offset:64
	v_mul_f32_e32 v44, v44, v234
	v_mul_f32_e32 v45, v45, v234
	v_mul_f32_e32 v46, v46, v234
	v_mul_f32_e32 v47, v47, v234
	v_cvt_pk_bf16_f32 v44, v44, v45
	v_cvt_pk_bf16_f32 v45, v46, v47
	ds_write_b64 v238, v[44:45] offset:96
	v_mul_f32_e32 v48, v48, v234
	v_mul_f32_e32 v49, v49, v234
	v_mul_f32_e32 v50, v50, v234
	v_mul_f32_e32 v51, v51, v234
	v_cvt_pk_bf16_f32 v48, v48, v49
	v_cvt_pk_bf16_f32 v49, v50, v51
	ds_write_b64 v238, v[48:49] offset:128
	v_mul_f32_e32 v52, v52, v234
	v_mul_f32_e32 v53, v53, v234
	v_mul_f32_e32 v54, v54, v234
	v_mul_f32_e32 v55, v55, v234
	v_cvt_pk_bf16_f32 v52, v52, v53
	v_cvt_pk_bf16_f32 v53, v54, v55
	ds_write_b64 v238, v[52:53] offset:160
	v_mul_f32_e32 v56, v56, v234
	v_mul_f32_e32 v57, v57, v234
	v_mul_f32_e32 v58, v58, v234
	v_mul_f32_e32 v59, v59, v234
	v_cvt_pk_bf16_f32 v56, v56, v57
	v_cvt_pk_bf16_f32 v57, v58, v59
	ds_write_b64 v238, v[56:57] offset:192
	v_mul_f32_e32 v60, v60, v234
	v_mul_f32_e32 v61, v61, v234
	v_mul_f32_e32 v62, v62, v234
	v_mul_f32_e32 v63, v63, v234
	v_cvt_pk_bf16_f32 v60, v60, v61
	v_cvt_pk_bf16_f32 v61, v62, v63
	ds_write_b64 v238, v[60:61] offset:224
	v_mul_f32_e32 v64, v64, v235
	v_mul_f32_e32 v65, v65, v235
	v_mul_f32_e32 v66, v66, v235
	v_mul_f32_e32 v67, v67, v235
	v_cvt_pk_bf16_f32 v64, v64, v65
	v_cvt_pk_bf16_f32 v65, v66, v67
	ds_write_b64 v238, v[64:65] offset:4352
	v_mul_f32_e32 v68, v68, v235
	v_mul_f32_e32 v69, v69, v235
	v_mul_f32_e32 v70, v70, v235
	v_mul_f32_e32 v71, v71, v235
	v_cvt_pk_bf16_f32 v68, v68, v69
	v_cvt_pk_bf16_f32 v69, v70, v71
	ds_write_b64 v238, v[68:69] offset:4384
	v_mul_f32_e32 v72, v72, v235
	v_mul_f32_e32 v73, v73, v235
	v_mul_f32_e32 v74, v74, v235
	v_mul_f32_e32 v75, v75, v235
	v_cvt_pk_bf16_f32 v72, v72, v73
	v_cvt_pk_bf16_f32 v73, v74, v75
	ds_write_b64 v238, v[72:73] offset:4416
	v_mul_f32_e32 v76, v76, v235
	v_mul_f32_e32 v77, v77, v235
	v_mul_f32_e32 v78, v78, v235
	v_mul_f32_e32 v79, v79, v235
	v_cvt_pk_bf16_f32 v76, v76, v77
	v_cvt_pk_bf16_f32 v77, v78, v79
	ds_write_b64 v238, v[76:77] offset:4448
	v_mul_f32_e32 v80, v80, v235
	v_mul_f32_e32 v81, v81, v235
	v_mul_f32_e32 v82, v82, v235
	v_mul_f32_e32 v83, v83, v235
	v_cvt_pk_bf16_f32 v80, v80, v81
	v_cvt_pk_bf16_f32 v81, v82, v83
	ds_write_b64 v238, v[80:81] offset:4480
	v_mul_f32_e32 v84, v84, v235
	v_mul_f32_e32 v85, v85, v235
	v_mul_f32_e32 v86, v86, v235
	v_mul_f32_e32 v87, v87, v235
	v_cvt_pk_bf16_f32 v84, v84, v85
	v_cvt_pk_bf16_f32 v85, v86, v87
	ds_write_b64 v238, v[84:85] offset:4512
	v_mul_f32_e32 v88, v88, v235
	v_mul_f32_e32 v89, v89, v235
	v_mul_f32_e32 v90, v90, v235
	v_mul_f32_e32 v91, v91, v235
	v_cvt_pk_bf16_f32 v88, v88, v89
	v_cvt_pk_bf16_f32 v89, v90, v91
	ds_write_b64 v238, v[88:89] offset:4544
	v_mul_f32_e32 v92, v92, v235
	v_mul_f32_e32 v93, v93, v235
	v_mul_f32_e32 v94, v94, v235
	v_mul_f32_e32 v95, v95, v235
	v_cvt_pk_bf16_f32 v92, v92, v93
	v_cvt_pk_bf16_f32 v93, v94, v95
	ds_write_b64 v238, v[92:93] offset:4576
	s_waitcnt lgkmcnt(0)
	v_and_b32_e32 v232, 63, v162
	v_lshrrev_b32_e32 v233, 1, v232
	v_and_b32_e32 v234, 1, v232
	v_mul_u32_u24_e32 v235, 0x110, v233
	v_lshl_add_u32 v235, v234, 7, v235
	v_add_u32_e32 v235, s0, v235
	ds_read_b128 v[128:131], v235 offset:0
	ds_read_b128 v[132:135], v235 offset:16
	ds_read_b128 v[136:139], v235 offset:32
	ds_read_b128 v[140:143], v235 offset:48
	ds_read_b128 v[144:147], v235 offset:64
	ds_read_b128 v[148:151], v235 offset:80
	ds_read_b128 v[152:155], v235 offset:96
	ds_read_b128 v[156:159], v235 offset:112
	s_lshl_b32 s0, s15, 12
	s_lshl_b32 s1, s19, 6
	s_add_i32 s0, s0, s1
	s_add_i32 s0, s0, s12
	v_add_u32_e32 v233, s0, v233
	v_lshlrev_b32_e32 v233, 12, v233
	v_lshl_add_u32 v233, v234, 7, v233
	s_lshl_b32 s1, s14, 8
	v_add_u32_e32 v233, s1, v233
	s_waitcnt lgkmcnt(7)
	global_store_dwordx4 v233, v[128:131], s[8:9] offset:0
	s_waitcnt lgkmcnt(6)
	global_store_dwordx4 v233, v[132:135], s[8:9] offset:16
	s_waitcnt lgkmcnt(5)
	global_store_dwordx4 v233, v[136:139], s[8:9] offset:32
	s_waitcnt lgkmcnt(4)
	global_store_dwordx4 v233, v[140:143], s[8:9] offset:48
	s_waitcnt lgkmcnt(3)
	global_store_dwordx4 v233, v[144:147], s[8:9] offset:64
	s_waitcnt lgkmcnt(2)
	global_store_dwordx4 v233, v[148:151], s[8:9] offset:80
	s_waitcnt lgkmcnt(1)
	global_store_dwordx4 v233, v[152:155], s[8:9] offset:96
	s_waitcnt lgkmcnt(0)
	global_store_dwordx4 v233, v[156:159], s[8:9] offset:112
	s_add_i32 s13, s13, s82
	s_branch .Lna_unit
